# G3_1 last round: 48 units split into 96 half units (128-row halves) on 96 CUs, half K loop without the second row-half MFMAs
# baseline (speedup 1.0000x reference)
.LBB0_331:
	s_lshl_b32 s1, s7, 5
	s_and_b32 s1, s1, 0x60
	s_lshl_b32 s86, s2, 6
	s_lshl_b32 s0, s2, 13
	s_lshl_b32 s7, s1, 7
	s_add_u32 s82, s16, 0x20100000
	s_addc_u32 s83, s17, 0
	s_add_i32 m0, s67, 0x18000
	v_lshl_add_u64 v[2:3], v[2:3], 0, s[94:95]
	s_waitcnt vmcnt(2)
	s_barrier
	global_load_lds_dwordx4 v[2:3], off
	v_lshl_add_u64 v[2:3], v[4:5], 0, s[94:95]
	s_add_i32 m0, s67, 0x1a000
	s_add_i32 s87, s67, 0x8000
	global_load_lds_dwordx4 v[2:3], off
	v_lshl_add_u64 v[2:3], v[10:11], 0, s[94:95]
	s_mov_b32 m0, s87
	s_add_i32 s2, s67, 0xa000
	global_load_lds_dwordx4 v[2:3], off
	v_lshl_add_u64 v[2:3], v[12:13], 0, s[94:95]
	s_mov_b32 m0, s2
	v_and_b32_e32 v188, 15, v222
	global_load_lds_dwordx4 v[2:3], off
	s_add_i32 m0, s67, 0x1c000
	v_lshl_add_u64 v[2:3], v[6:7], 0, s[94:95]
	global_load_lds_dwordx4 v[2:3], off
	v_lshl_add_u64 v[2:3], v[8:9], 0, s[94:95]
	s_add_i32 m0, s67, 0x1e000
	v_lshlrev_b32_e32 v4, 2, v222
	global_load_lds_dwordx4 v[2:3], off
	v_bfe_u32 v2, v222, 4, 2
	v_lshlrev_b32_e32 v3, 4, v2
	s_cmpk_lt_u32 s9, 0x100
	v_lshl_or_b32 v3, v188, 6, v3
	v_and_b32_e32 v4, 32, v4
	s_cselect_b64 s[84:85], -1, 0
	s_lshl_b32 s35, s35, 3
	v_bitop3_b32 v5, v3, s0, v4 bitop3:0xde
	v_bitop3_b32 v223, s7, v3, v4 bitop3:0xf6
	v_cvt_f32_u32_e32 v3, s35
	v_cmp_gt_u32_e64 s[14:15], 2, v188
	s_lshr_b32 s73, s3, 6
	s_lshr_b32 s3, s3, 10
	v_writelane_b32 v245, s14, 62
	s_and_b32 s34, s34, 4
	s_lshr_b32 s0, s8, 3
	v_writelane_b32 v245, s15, 63
	s_add_u32 s14, s92, 0x5800
	v_rcp_iflag_f32_e32 v3, v3
	s_addc_u32 s15, s93, 0
	v_writelane_b32 v244, s14, 30
	v_add_u32_e32 v0, v18, v0
	v_mul_f32_e32 v3, 0x4f7ffffe, v3
	v_writelane_b32 v244, s15, 31
	s_add_u32 s14, s92, 0xb000
	s_addc_u32 s15, s93, 0
	v_writelane_b32 v244, s14, 32
	v_cvt_u32_f32_e32 v3, v3
	v_writelane_b32 v245, s0, 60
	v_writelane_b32 v244, s15, 33
	s_add_u32 s14, s16, 0x20d60000
	s_addc_u32 s15, s17, 0
	s_add_u32 s74, s16, 0x219c0000
	s_addc_u32 s75, s17, 0
	v_lshl_or_b32 v224, v2, 3, s1
	v_lshl_or_b32 v225, v2, 2, s1
	s_sub_i32 s0, 0, s35
	v_readfirstlane_b32 s1, v3
	v_add_lshl_u32 v0, v0, v17, 1
	s_waitcnt vmcnt(6)
	s_mul_i32 s0, s0, s1
	v_lshl_add_u64 v[192:193], s[90:91], 0, v[0:1]
	v_add_u32_e32 v0, v16, v14
	v_writelane_b32 v244, s14, 34
	s_mul_hi_u32 s0, s1, s0
	v_add_lshl_u32 v0, v0, v15, 1
	v_cmp_lt_u32_e64 s[42:43], 1, v188
	v_cmp_lt_u32_e64 s[44:45], 13, v188
	v_add_u32_e32 v190, -14, v188
	s_mov_b32 s7, s89
	s_mov_b32 s9, s89
	v_writelane_b32 v244, s15, 35
	s_mov_b32 s80, 0
	s_mov_b32 s100, 0
	s_mov_b32 s101, 0
	s_add_i32 s0, s1, s0
	v_lshl_add_u64 v[194:195], s[90:91], 0, v[0:1]
	v_add_u32_e32 v226, 0, v5
	s_barrier
	v_writelane_b32 v244, s0, 36
	s_branch .LBB0_334
.Lhk_344:
	s_add_i32 vcc_lo, s50, 2
	s_add_u32 s68, s48, 0x80
	s_addc_u32 s51, s49, 0
	s_add_i32 s70, 0, 0x10000
	s_cmp_eq_u32 s15, s50
	s_cselect_b32 s51, s1, s51
	s_cselect_b32 s50, s0, s68
	v_add_u32_e32 v0, s70, v223
	s_cselect_b32 s69, s53, s57
	s_cselect_b32 s68, s52, s56
	s_add_i32 s71, 0, 0x14000
	ds_read_b128 v[130:133], v0
	ds_read_b128 v[134:137], v0 offset:1024
	ds_read_b128 v[138:141], v0 offset:2048
	ds_read_b128 v[142:145], v0 offset:3072
	v_add_u32_e32 v0, s71, v223
	ds_read_b128 v[146:149], v0
	ds_read_b128 v[150:153], v0 offset:1024
	ds_read_b128 v[154:157], v0 offset:2048
	ds_read_b128 v[158:161], v0 offset:3072
	v_lshl_add_u64 v[212:213], s[48:49], 0, v[192:193]
	s_add_i32 m0, s67, 0xc000
	ds_read_b128 v[162:165], v226
	ds_read_b128 v[166:169], v226 offset:1024
	ds_read_b128 v[170:173], v226 offset:2048
	ds_read_b128 v[174:177], v226 offset:3072
	ds_read_b128 v[196:199], v226 offset:4096
	ds_read_b128 v[200:203], v226 offset:5120
	ds_read_b128 v[204:207], v226 offset:6144
	ds_read_b128 v[208:211], v226 offset:7168
	global_load_lds_dwordx4 v[212:213], off
	v_lshl_add_u64 v[212:213], s[48:49], 0, v[194:195]
	s_add_i32 m0, s67, 0xe000
	s_nop 0
	global_load_lds_dwordx4 v[212:213], off
	s_waitcnt vmcnt(8)
	s_waitcnt lgkmcnt(0)
	s_barrier
	s_setprio 1
	s_waitcnt lgkmcnt(0)
	v_mfma_f32_16x16x32_bf16 v[126:129], v[130:133], v[162:165], v[126:129]
	v_mfma_f32_16x16x32_bf16 v[122:125], v[138:141], v[162:165], v[122:125]
	v_mfma_f32_16x16x32_bf16 v[118:121], v[130:133], v[170:173], v[118:121]
	v_mfma_f32_16x16x32_bf16 v[114:117], v[138:141], v[170:173], v[114:117]
	v_mfma_f32_16x16x32_bf16 v[102:105], v[130:133], v[196:199], v[102:105]
	v_mfma_f32_16x16x32_bf16 v[98:101], v[138:141], v[196:199], v[98:101]
	v_mfma_f32_16x16x32_bf16 v[86:89], v[130:133], v[204:207], v[86:89]
	v_mfma_f32_16x16x32_bf16 v[82:85], v[138:141], v[204:207], v[82:85]
	v_mfma_f32_16x16x32_bf16 v[126:129], v[134:137], v[166:169], v[126:129]
	v_mfma_f32_16x16x32_bf16 v[122:125], v[142:145], v[166:169], v[122:125]
	v_mfma_f32_16x16x32_bf16 v[118:121], v[134:137], v[174:177], v[118:121]
	v_mfma_f32_16x16x32_bf16 v[114:117], v[142:145], v[174:177], v[114:117]
	v_mfma_f32_16x16x32_bf16 v[102:105], v[134:137], v[200:203], v[102:105]
	v_mfma_f32_16x16x32_bf16 v[98:101], v[142:145], v[200:203], v[98:101]
	v_mfma_f32_16x16x32_bf16 v[86:89], v[134:137], v[208:211], v[86:89]
	v_mfma_f32_16x16x32_bf16 v[82:85], v[142:145], v[208:211], v[82:85]
	s_setprio 0
	s_setprio 1
	v_mfma_f32_16x16x32_bf16 v[110:113], v[146:149], v[162:165], v[110:113]
	v_mfma_f32_16x16x32_bf16 v[106:109], v[154:157], v[162:165], v[106:109]
	v_mfma_f32_16x16x32_bf16 v[94:97], v[146:149], v[170:173], v[94:97]
	v_mfma_f32_16x16x32_bf16 v[90:93], v[154:157], v[170:173], v[90:93]
	v_mfma_f32_16x16x32_bf16 v[78:81], v[146:149], v[196:199], v[78:81]
	v_mfma_f32_16x16x32_bf16 v[74:77], v[154:157], v[196:199], v[74:77]
	v_mfma_f32_16x16x32_bf16 v[70:73], v[146:149], v[204:207], v[70:73]
	v_mfma_f32_16x16x32_bf16 v[66:69], v[154:157], v[204:207], v[66:69]
	v_mfma_f32_16x16x32_bf16 v[110:113], v[150:153], v[166:169], v[110:113]
	v_mfma_f32_16x16x32_bf16 v[106:109], v[158:161], v[166:169], v[106:109]
	v_mfma_f32_16x16x32_bf16 v[94:97], v[150:153], v[174:177], v[94:97]
	v_mfma_f32_16x16x32_bf16 v[90:93], v[158:161], v[174:177], v[90:93]
	v_mfma_f32_16x16x32_bf16 v[78:81], v[150:153], v[200:203], v[78:81]
	v_mfma_f32_16x16x32_bf16 v[74:77], v[158:161], v[200:203], v[74:77]
	v_mfma_f32_16x16x32_bf16 v[70:73], v[150:153], v[208:211], v[70:73]
	v_mfma_f32_16x16x32_bf16 v[66:69], v[158:161], v[208:211], v[66:69]
	s_setprio 0
	s_barrier
	s_add_i32 s70, s70, s63
	v_lshl_add_u64 v[212:213], s[68:69], 0, v[186:187]
	s_mov_b32 m0, s70
	global_load_lds_dwordx4 v[212:213], off
	s_add_i32 m0, s70, 0x2000
	v_lshl_add_u64 v[214:215], s[68:69], 0, v[182:183]
	s_add_u32 s68, s68, s90
	s_addc_u32 s69, s69, 0
	s_add_i32 s70, s71, s63
	global_load_lds_dwordx4 v[214:215], off
	v_lshl_add_u64 v[216:217], s[68:69], 0, v[186:187]
	s_mov_b32 m0, s70
	v_lshl_add_u64 v[218:219], s[68:69], 0, v[182:183]
	global_load_lds_dwordx4 v[216:217], off
	s_add_i32 m0, s70, 0x2000
	v_lshl_add_u64 v[232:233], s[50:51], 0, v[184:185]
	global_load_lds_dwordx4 v[218:219], off
	s_mov_b32 m0, s67
	v_lshl_add_u64 v[234:235], s[50:51], 0, v[180:181]
	global_load_lds_dwordx4 v[232:233], off
	s_mov_b32 m0, s33
	s_nop 0
	global_load_lds_dwordx4 v[234:235], off
	s_waitcnt vmcnt(8)
	s_waitcnt lgkmcnt(0)
	s_barrier
	s_setprio 1
	s_waitcnt lgkmcnt(0)
	s_setprio 0
	s_setprio 1
	s_setprio 0
	s_barrier
	s_add_i32 s68, 0, 0x18000
	v_add_u32_e32 v0, s68, v223
	s_add_i32 s69, 0, 0x1c000
	ds_read_b128 v[130:133], v0
	ds_read_b128 v[134:137], v0 offset:1024
	ds_read_b128 v[138:141], v0 offset:2048
	ds_read_b128 v[142:145], v0 offset:3072
	v_add_u32_e32 v0, s69, v223
	ds_read_b128 v[146:149], v0
	ds_read_b128 v[150:153], v0 offset:1024
	ds_read_b128 v[154:157], v0 offset:2048
	ds_read_b128 v[158:161], v0 offset:3072
	s_add_u32 s50, s50, s90
	s_addc_u32 s51, s51, 0
	s_mov_b32 m0, s65
	v_lshl_add_u64 v[236:237], s[50:51], 0, v[184:185]
	ds_read_b128 v[162:165], v226 offset:32768
	ds_read_b128 v[166:169], v226 offset:33792
	ds_read_b128 v[170:173], v226 offset:34816
	ds_read_b128 v[174:177], v226 offset:35840
	ds_read_b128 v[196:199], v226 offset:36864
	ds_read_b128 v[200:203], v226 offset:37888
	ds_read_b128 v[204:207], v226 offset:38912
	ds_read_b128 v[208:211], v226 offset:39936
	global_load_lds_dwordx4 v[236:237], off
	v_lshl_add_u64 v[236:237], s[50:51], 0, v[180:181]
	s_mov_b32 m0, s22
	s_nop 0
	global_load_lds_dwordx4 v[236:237], off
	s_waitcnt vmcnt(8)
	s_waitcnt lgkmcnt(0)
	s_barrier
	s_setprio 1
	s_waitcnt lgkmcnt(0)
	v_mfma_f32_16x16x32_bf16 v[126:129], v[130:133], v[162:165], v[126:129]
	v_mfma_f32_16x16x32_bf16 v[122:125], v[138:141], v[162:165], v[122:125]
	v_mfma_f32_16x16x32_bf16 v[118:121], v[130:133], v[170:173], v[118:121]
	v_mfma_f32_16x16x32_bf16 v[114:117], v[138:141], v[170:173], v[114:117]
	v_mfma_f32_16x16x32_bf16 v[102:105], v[130:133], v[196:199], v[102:105]
	v_mfma_f32_16x16x32_bf16 v[98:101], v[138:141], v[196:199], v[98:101]
	v_mfma_f32_16x16x32_bf16 v[86:89], v[130:133], v[204:207], v[86:89]
	v_mfma_f32_16x16x32_bf16 v[82:85], v[138:141], v[204:207], v[82:85]
	v_mfma_f32_16x16x32_bf16 v[126:129], v[134:137], v[166:169], v[126:129]
	v_mfma_f32_16x16x32_bf16 v[122:125], v[142:145], v[166:169], v[122:125]
	v_mfma_f32_16x16x32_bf16 v[118:121], v[134:137], v[174:177], v[118:121]
	v_mfma_f32_16x16x32_bf16 v[114:117], v[142:145], v[174:177], v[114:117]
	v_mfma_f32_16x16x32_bf16 v[102:105], v[134:137], v[200:203], v[102:105]
	v_mfma_f32_16x16x32_bf16 v[98:101], v[142:145], v[200:203], v[98:101]
	v_mfma_f32_16x16x32_bf16 v[86:89], v[134:137], v[208:211], v[86:89]
	v_mfma_f32_16x16x32_bf16 v[82:85], v[142:145], v[208:211], v[82:85]
	s_setprio 0
	s_setprio 1
	v_mfma_f32_16x16x32_bf16 v[110:113], v[146:149], v[162:165], v[110:113]
	v_mfma_f32_16x16x32_bf16 v[106:109], v[154:157], v[162:165], v[106:109]
	v_mfma_f32_16x16x32_bf16 v[94:97], v[146:149], v[170:173], v[94:97]
	v_mfma_f32_16x16x32_bf16 v[90:93], v[154:157], v[170:173], v[90:93]
	v_mfma_f32_16x16x32_bf16 v[78:81], v[146:149], v[196:199], v[78:81]
	v_mfma_f32_16x16x32_bf16 v[74:77], v[154:157], v[196:199], v[74:77]
	v_mfma_f32_16x16x32_bf16 v[70:73], v[146:149], v[204:207], v[70:73]
	v_mfma_f32_16x16x32_bf16 v[66:69], v[154:157], v[204:207], v[66:69]
	v_mfma_f32_16x16x32_bf16 v[110:113], v[150:153], v[166:169], v[110:113]
	v_mfma_f32_16x16x32_bf16 v[106:109], v[158:161], v[166:169], v[106:109]
	v_mfma_f32_16x16x32_bf16 v[94:97], v[150:153], v[174:177], v[94:97]
	v_mfma_f32_16x16x32_bf16 v[90:93], v[158:161], v[174:177], v[90:93]
	v_mfma_f32_16x16x32_bf16 v[78:81], v[150:153], v[200:203], v[78:81]
	v_mfma_f32_16x16x32_bf16 v[74:77], v[158:161], v[200:203], v[74:77]
	v_mfma_f32_16x16x32_bf16 v[70:73], v[150:153], v[208:211], v[70:73]
	v_mfma_f32_16x16x32_bf16 v[66:69], v[158:161], v[208:211], v[66:69]
	s_setprio 0
	s_barrier
	s_add_i32 s50, s68, s63
	v_lshl_add_u64 v[212:213], v[212:213], 0, s[94:95]
	s_mov_b32 m0, s50
	global_load_lds_dwordx4 v[212:213], off
	v_lshl_add_u64 v[212:213], v[214:215], 0, s[94:95]
	s_add_i32 m0, s50, 0x2000
	s_add_i32 s50, s69, s63
	global_load_lds_dwordx4 v[212:213], off
	v_lshl_add_u64 v[212:213], v[216:217], 0, s[94:95]
	s_mov_b32 m0, s50
	s_nop 0
	global_load_lds_dwordx4 v[212:213], off
	v_lshl_add_u64 v[212:213], v[218:219], 0, s[94:95]
	s_add_i32 m0, s50, 0x2000
	s_nop 0
	global_load_lds_dwordx4 v[212:213], off
	v_lshl_add_u64 v[212:213], v[232:233], 0, s[94:95]
	s_mov_b32 m0, s87
	s_nop 0
	global_load_lds_dwordx4 v[212:213], off
	v_lshl_add_u64 v[212:213], v[234:235], 0, s[94:95]
	s_mov_b32 m0, s2
	s_nop 0
	global_load_lds_dwordx4 v[212:213], off
	s_waitcnt vmcnt(8)
	s_waitcnt lgkmcnt(0)
	s_barrier
	s_setprio 1
	s_waitcnt lgkmcnt(0)
	s_setprio 0
	s_setprio 1
	s_setprio 0
	s_barrier
	s_add_u32 s48, s48, 0x100
	s_addc_u32 s49, s49, 0
	s_add_u32 s56, s56, 0x100
	s_addc_u32 s57, s57, 0
	s_cmp_ge_i32 vcc_lo, s55
	s_mov_b32 s50, vcc_lo
	s_cbranch_scc0 .Lhk_344
	s_branch .Lk_exit

.LBB0_333:
	s_andn2_b64 vcc, exec, s[46:47]
	s_mov_b32 s88, s81
	s_mov_b32 s55, s41
	s_mov_b32 s23, s91
	s_mov_b32 s54, s40
	s_mov_b32 s100, s101
	s_mov_b64 s[50:51], s[52:53]
	s_mov_b64 s[48:49], s[0:1]
	s_cbranch_vccz .LBB0_498
.LBB0_334:
	s_add_i32 s80, s80, 1
	s_mul_i32 s0, s80, s37
	s_mul_hi_u32 s1, s80, s36
	s_add_i32 s1, s1, s0
	s_mul_i32 s0, s80, s36
	v_readlane_b32 s46, v246, 59
	v_readlane_b32 s47, v246, 60
	s_add_u32 s46, s0, s46
	s_addc_u32 s47, s1, s47
	s_mov_b32 s101, 0
	v_readlane_b32 s99, v246, 1
	s_nop 0
	s_cmp_eq_u32 s99, 16
	s_cbranch_scc0 .Lhu_no
	s_cmpk_eq_u32 s36, 0x100
	s_cbranch_scc0 .Lhu_no
	s_cmpk_eq_u32 s6, 0x630
	s_cbranch_scc0 .Lhu_no
	s_cmp_eq_u32 s80, 6
	s_cbranch_scc0 .Lhu_no
	v_readlane_b32 s99, v246, 59
	s_nop 0
	s_cmp_lt_u32 s99, 96
	s_cbranch_scc1 .Lhu_in
	s_mov_b32 s46, s6
	s_mov_b32 s47, 0
	s_branch .Lhu_no
.Lhu_in:
	s_cmp_ge_u32 s99, 48
	s_cselect_b32 s101, 1, 0
	s_cselect_b32 s98, 48, 0
	s_sub_u32 s99, s99, s98
	s_add_u32 s46, s99, 0x600
	s_mov_b32 s47, 0
.Lhu_no:
	v_mov_b64_e32 v[2:3], s[6:7]
	v_cmp_ge_i64_e32 vcc, s[46:47], v[2:3]
	v_cmp_lt_i64_e64 s[0:1], s[46:47], v[2:3]
	s_cbranch_vccnz .LBB0_339
	v_mov_b64_e32 v[2:3], s[8:9]
	v_cmp_lt_i64_e32 vcc, s[46:47], v[2:3]
	s_mov_b64 s[52:53], -1
	s_and_b64 vcc, exec, vcc
	s_cbranch_vccnz .LBB0_337
	s_sub_i32 s14, s46, s8
	s_ashr_i32 s81, s14, 5
	s_bfe_u32 s14, s14, 0x20003
	s_or_b32 s40, s14, 32
	s_and_b32 s91, s46, 7
	s_cmp_lt_i32 s81, s34
	s_mul_i32 s14, s81, s3
	s_cselect_b64 s[52:53], -1, 0
	s_min_i32 s15, s81, s34
	s_add_i32 s14, s14, s15
	s_cmp_lg_u64 s[52:53], 0
	s_addc_u32 s15, s3, 0
	s_lshl_b32 s41, s15, 1
	s_mov_b64 s[52:53], 0

.LBB0_339:
	s_nop 0
	v_cndmask_b32_e64 v0, 0, 1, s[0:1]
	v_cmp_ne_u32_e64 s[46:47], 1, v0
	s_andn2_b64 vcc, exec, s[0:1]
	s_mov_b64 s[0:1], s[48:49]
	s_cbranch_vccnz .LBB0_341
	s_mul_i32 s1, s59, s40
	s_mul_hi_i32 s0, s59, s40
	s_add_u32 s52, s12, s1
	s_addc_u32 s53, s13, s0
	s_ashr_i32 s15, s14, 31
	s_lshl_b64 s[0:1], s[14:15], 8
	s_add_u32 s0, s52, s0
	s_addc_u32 s1, s53, s1
	s_cmp_eq_u32 s101, 1
	s_cselect_b32 s98, s90, 0
	s_add_u32 s0, s0, s98
	s_addc_u32 s1, s1, 0

.LBB0_343:
	s_add_i32 s15, s55, -2
	s_add_u32 s48, s48, 0x80
	s_addc_u32 s49, s49, 0
	s_add_u32 s56, s50, 0x100
	v_mov_b32_e32 v2, 0
	s_addc_u32 s57, s51, 0
	s_mov_b32 s50, 0
	v_mov_b32_e32 v3, v2
	v_mov_b32_e32 v4, v2
	v_mov_b32_e32 v5, v2
	v_mov_b32_e32 v6, v2
	v_mov_b32_e32 v7, v2
	v_mov_b32_e32 v8, v2
	v_mov_b32_e32 v9, v2
	v_mov_b32_e32 v10, v2
	v_mov_b32_e32 v11, v2
	v_mov_b32_e32 v12, v2
	v_mov_b32_e32 v13, v2
	v_mov_b32_e32 v14, v2
	v_mov_b32_e32 v15, v2
	v_mov_b32_e32 v16, v2
	v_mov_b32_e32 v17, v2
	v_mov_b32_e32 v26, v2
	v_mov_b32_e32 v27, v2
	v_mov_b32_e32 v28, v2
	v_mov_b32_e32 v29, v2
	v_mov_b32_e32 v30, v2
	v_mov_b32_e32 v31, v2
	v_mov_b32_e32 v32, v2
	v_mov_b32_e32 v33, v2
	v_mov_b32_e32 v42, v2
	v_mov_b32_e32 v43, v2
	v_mov_b32_e32 v44, v2
	v_mov_b32_e32 v45, v2
	v_mov_b32_e32 v46, v2
	v_mov_b32_e32 v47, v2
	v_mov_b32_e32 v48, v2
	v_mov_b32_e32 v49, v2
	v_mov_b32_e32 v18, v2
	v_mov_b32_e32 v19, v2
	v_mov_b32_e32 v20, v2
	v_mov_b32_e32 v21, v2
	v_mov_b32_e32 v22, v2
	v_mov_b32_e32 v23, v2
	v_mov_b32_e32 v24, v2
	v_mov_b32_e32 v25, v2
	v_mov_b32_e32 v34, v2
	v_mov_b32_e32 v35, v2
	v_mov_b32_e32 v36, v2
	v_mov_b32_e32 v37, v2
	v_mov_b32_e32 v38, v2
	v_mov_b32_e32 v39, v2
	v_mov_b32_e32 v40, v2
	v_mov_b32_e32 v41, v2
	v_mov_b32_e32 v50, v2
	v_mov_b32_e32 v51, v2
	v_mov_b32_e32 v52, v2
	v_mov_b32_e32 v53, v2
	v_mov_b32_e32 v54, v2
	v_mov_b32_e32 v55, v2
	v_mov_b32_e32 v56, v2
	v_mov_b32_e32 v57, v2
	v_mov_b32_e32 v58, v2
	v_mov_b32_e32 v59, v2
	v_mov_b32_e32 v60, v2
	v_mov_b32_e32 v61, v2
	v_mov_b32_e32 v62, v2
	v_mov_b32_e32 v63, v2
	v_mov_b32_e32 v64, v2
	v_mov_b32_e32 v65, v2
	v_mov_b32_e32 v66, v2
	v_mov_b32_e32 v67, v2
	v_mov_b32_e32 v68, v2
	v_mov_b32_e32 v69, v2
	v_mov_b32_e32 v70, v2
	v_mov_b32_e32 v71, v2
	v_mov_b32_e32 v72, v2
	v_mov_b32_e32 v73, v2
	v_mov_b32_e32 v74, v2
	v_mov_b32_e32 v75, v2
	v_mov_b32_e32 v76, v2
	v_mov_b32_e32 v77, v2
	v_mov_b32_e32 v78, v2
	v_mov_b32_e32 v79, v2
	v_mov_b32_e32 v80, v2
	v_mov_b32_e32 v81, v2
	v_mov_b32_e32 v90, v2
	v_mov_b32_e32 v91, v2
	v_mov_b32_e32 v92, v2
	v_mov_b32_e32 v93, v2
	v_mov_b32_e32 v94, v2
	v_mov_b32_e32 v95, v2
	v_mov_b32_e32 v96, v2
	v_mov_b32_e32 v97, v2
	v_mov_b32_e32 v106, v2
	v_mov_b32_e32 v107, v2
	v_mov_b32_e32 v108, v2
	v_mov_b32_e32 v109, v2
	v_mov_b32_e32 v110, v2
	v_mov_b32_e32 v111, v2
	v_mov_b32_e32 v112, v2
	v_mov_b32_e32 v113, v2
	v_mov_b32_e32 v82, v2
	v_mov_b32_e32 v83, v2
	v_mov_b32_e32 v84, v2
	v_mov_b32_e32 v85, v2
	v_mov_b32_e32 v86, v2
	v_mov_b32_e32 v87, v2
	v_mov_b32_e32 v88, v2
	v_mov_b32_e32 v89, v2
	v_mov_b32_e32 v98, v2
	v_mov_b32_e32 v99, v2
	v_mov_b32_e32 v100, v2
	v_mov_b32_e32 v101, v2
	v_mov_b32_e32 v102, v2
	v_mov_b32_e32 v103, v2
	v_mov_b32_e32 v104, v2
	v_mov_b32_e32 v105, v2
	v_mov_b32_e32 v114, v2
	v_mov_b32_e32 v115, v2
	v_mov_b32_e32 v116, v2
	v_mov_b32_e32 v117, v2
	v_mov_b32_e32 v118, v2
	v_mov_b32_e32 v119, v2
	v_mov_b32_e32 v120, v2
	v_mov_b32_e32 v121, v2
	v_mov_b32_e32 v122, v2
	v_mov_b32_e32 v123, v2
	v_mov_b32_e32 v124, v2
	v_mov_b32_e32 v125, v2
	v_mov_b32_e32 v126, v2
	v_mov_b32_e32 v127, v2
	v_mov_b32_e32 v128, v2
	v_mov_b32_e32 v129, v2
	s_cmp_eq_u32 s100, 1
	s_cbranch_scc1 .Lhk_344

.Lk_exit:
	s_and_b64 vcc, exec, s[84:85]
	s_cbranch_vccz .LBB0_347
	s_barrier
.LBB0_347:
	s_lshl_b32 s15, s54, 8
	s_add_i32 s15, s15, s86
	s_lshl_b32 s98, s100, 7
	s_add_i32 s15, s15, s98
	v_or_b32_e32 v196, s15, v188
	s_cmp_lt_i32 s58, 2
	s_mov_b64 s[48:49], -1
	s_cbranch_scc1 .LBB0_388
	s_cmp_gt_i32 s58, 2
	s_cbranch_scc0 .LBB0_374
	v_lshl_or_b32 v162, s23, 7, v224
	v_ashrrev_i32_e32 v163, 31, v162
	v_readlane_b32 s48, v244, 30
	v_lshlrev_b64 v[164:165], 2, v[162:163]
	v_readlane_b32 s49, v244, 31
	v_lshl_add_u64 v[134:135], s[92:93], 0, v[164:165]
	v_lshl_add_u64 v[158:159], s[26:27], 0, v[164:165]
	v_lshl_add_u64 v[138:139], s[48:49], 0, v[164:165]
	v_readlane_b32 s48, v244, 32
	v_readlane_b32 s49, v244, 33
	global_load_dwordx4 v[130:133], v[134:135], off offset:16
	global_load_dwordx4 v[146:149], v[134:135], off
	v_lshl_add_u64 v[142:143], s[48:49], 0, v[164:165]
	global_load_dwordx4 v[134:137], v[138:139], off offset:16
	global_load_dwordx4 v[150:153], v[138:139], off
	s_nop 0
	global_load_dwordx4 v[138:141], v[142:143], off offset:16
	global_load_dwordx4 v[154:157], v[142:143], off
	s_nop 0
	global_load_dwordx4 v[142:145], v[158:159], off offset:16
	s_nop 0
	global_load_dwordx4 v[158:161], v[158:159], off
	v_mov_b32_e32 v199, v1
	v_mov_b32_e32 v201, v1
	s_nop 0
	v_mov_b32_dpp v199, v199 row_ror:1 row_mask:0xf bank_mask:0xf
	v_mov_b32_dpp v201, v201 row_ror:2 row_mask:0xf bank_mask:0xf
	v_mov_b32_e32 v166, v199
	v_mov_b32_e32 v168, v201
	v_mov_b32_e32 v167, v199
	v_mov_b32_e32 v169, v201
	v_mov_b32_e32 v170, v199
	v_mov_b32_e32 v172, v201
	v_mov_b32_e32 v171, v199
	v_mov_b32_e32 v173, v201
	v_mov_b32_e32 v174, v199
	v_mov_b32_e32 v176, v201
	v_mov_b32_e32 v175, v199
	v_mov_b32_e32 v177, v201
	v_mov_b32_e32 v198, v199
	v_mov_b32_e32 v200, v201
	v_mov_b32_dpp v166, v126 row_shr:1 row_mask:0xf bank_mask:0xf
	v_mov_b32_dpp v168, v126 row_shr:2 row_mask:0xf bank_mask:0xf
	v_mov_b32_dpp v167, v127 row_shr:1 row_mask:0xf bank_mask:0xf
	v_mov_b32_dpp v169, v127 row_shr:2 row_mask:0xf bank_mask:0xf
	v_mov_b32_dpp v170, v128 row_shr:1 row_mask:0xf bank_mask:0xf
	v_mov_b32_dpp v172, v128 row_shr:2 row_mask:0xf bank_mask:0xf
	v_mov_b32_dpp v171, v129 row_shr:1 row_mask:0xf bank_mask:0xf
	v_mov_b32_dpp v173, v129 row_shr:2 row_mask:0xf bank_mask:0xf
	v_mov_b32_dpp v174, v122 row_shr:1 row_mask:0xf bank_mask:0xf
	v_mov_b32_dpp v176, v122 row_shr:2 row_mask:0xf bank_mask:0xf
	v_mov_b32_dpp v175, v123 row_shr:1 row_mask:0xf bank_mask:0xf
	v_mov_b32_dpp v177, v123 row_shr:2 row_mask:0xf bank_mask:0xf
	v_mov_b32_dpp v198, v124 row_shr:1 row_mask:0xf bank_mask:0xf
	v_mov_b32_dpp v200, v124 row_shr:2 row_mask:0xf bank_mask:0xf
	v_mov_b32_dpp v199, v125 row_shr:1 row_mask:0xf bank_mask:0xf
	v_mov_b32_dpp v201, v125 row_shr:2 row_mask:0xf bank_mask:0xf
	s_and_saveexec_b64 s[48:49], s[42:43]
	s_xor_b64 s[48:49], exec, s[48:49]
	s_movk_i32 s70, 0x5800
	s_cbranch_execz .LBB0_351
	s_waitcnt vmcnt(0)
	v_pk_fma_f32 v[200:201], v[132:133], v[200:201], v[144:145]
	v_pk_fma_f32 v[176:177], v[130:131], v[176:177], v[142:143]
	v_pk_fma_f32 v[198:199], v[136:137], v[198:199], v[200:201]
	v_pk_fma_f32 v[174:175], v[134:135], v[174:175], v[176:177]
	v_pk_fma_f32 v[198:199], v[124:125], v[140:141], v[198:199]
	v_pk_fma_f32 v[174:175], v[122:123], v[138:139], v[174:175]
	v_mul_f32_e32 v0, 0xbfb8aa3b, v198
	v_exp_f32_e32 v0, v0
	v_mul_f32_e32 v197, 0xbfb8aa3b, v199
	v_exp_f32_e32 v197, v197
	v_pk_fma_f32 v[172:173], v[148:149], v[172:173], v[160:161]
	v_add_f32_e32 v0, 1.0, v0
	v_rcp_f32_e32 v200, v0
	v_add_f32_e32 v197, 1.0, v197
	v_mul_f32_e32 v0, 0xbfb8aa3b, v174
	v_rcp_f32_e32 v201, v197
	v_exp_f32_e32 v0, v0
	v_mul_f32_e32 v197, 0xbfb8aa3b, v175
	v_exp_f32_e32 v197, v197
	v_pk_fma_f32 v[170:171], v[152:153], v[170:171], v[172:173]
	v_add_f32_e32 v0, 1.0, v0
	v_pk_mul_f32 v[176:177], v[198:199], v[200:201]
	v_rcp_f32_e32 v198, v0
	v_add_f32_e32 v0, 1.0, v197
	v_pk_fma_f32 v[170:171], v[128:129], v[156:157], v[170:171]
	v_pk_fma_f32 v[168:169], v[146:147], v[168:169], v[158:159]
	v_rcp_f32_e32 v199, v0
	v_mul_f32_e32 v0, 0xbfb8aa3b, v170
	v_pk_fma_f32 v[166:167], v[150:151], v[166:167], v[168:169]
	v_exp_f32_e32 v0, v0
	v_mul_f32_e32 v172, 0xbfb8aa3b, v171
	v_pk_fma_f32 v[166:167], v[126:127], v[154:155], v[166:167]
	v_exp_f32_e32 v197, v172
	v_mul_f32_e32 v168, 0xbfb8aa3b, v166
	v_exp_f32_e32 v168, v168
	v_mul_f32_e32 v169, 0xbfb8aa3b, v167
	v_exp_f32_e32 v169, v169
	v_add_f32_e32 v0, 1.0, v0
	v_pk_mul_f32 v[172:173], v[174:175], v[198:199]
	v_rcp_f32_e32 v174, v0
	v_add_f32_e32 v0, 1.0, v197
	v_rcp_f32_e32 v175, v0
	v_add_f32_e32 v0, 1.0, v168
	v_rcp_f32_e32 v168, v0
	v_add_f32_e32 v0, 1.0, v169
	v_rcp_f32_e32 v169, v0
	v_pk_mul_f32 v[170:171], v[170:171], v[174:175]
	s_movk_i32 s50, 0x2c00
	v_pk_mul_f32 v[170:171], v[112:113], v[170:171]
	v_pk_mul_f32 v[166:167], v[166:167], v[168:169]
	v_pk_mul_f32 v[176:177], v[108:109], v[176:177]
	v_pk_mul_f32 v[166:167], v[110:111], v[166:167]
	v_pk_mul_f32 v[172:173], v[106:107], v[172:173]
	v_cvt_pk_bf16_f32 v166, v166, v167
	v_cvt_pk_bf16_f32 v167, v170, v171
	v_mov_b64_e32 v[170:171], s[24:25]
	v_mad_i64_i32 v[170:171], s[50:51], v196, s50, v[170:171]
	v_cvt_pk_bf16_f32 v168, v172, v173
	v_cvt_pk_bf16_f32 v169, v176, v177
	v_lshl_add_u64 v[170:171], v[162:163], 1, v[170:171]
	global_store_dwordx4 v[170:171], v[166:169], off

.LBB0_361:
	s_or_b64 exec, exec, s[56:57]
	s_cmp_eq_u32 s100, 1
	s_cbranch_scc1 .Lhu_skip_ai1
	v_mov_b32_e32 v203, v1
	v_mov_b32_e32 v205, v1
	v_add_u32_e32 v0, 0x80, v196
	v_mov_b32_dpp v203, v203 row_ror:1 row_mask:0xf bank_mask:0xf
	v_mov_b32_dpp v205, v205 row_ror:2 row_mask:0xf bank_mask:0xf
	v_mov_b32_e32 v170, v203
	v_mov_b32_e32 v172, v205
	v_mov_b32_e32 v171, v203
	v_mov_b32_e32 v173, v205
	v_mov_b32_e32 v174, v203
	v_mov_b32_e32 v176, v205
	v_mov_b32_e32 v175, v203
	v_mov_b32_e32 v177, v205
	v_mov_b32_e32 v198, v203
	v_mov_b32_e32 v200, v205
	v_mov_b32_e32 v199, v203
	v_mov_b32_e32 v201, v205
	v_mov_b32_e32 v202, v203
	v_mov_b32_e32 v204, v205
	v_mov_b32_dpp v170, v62 row_shr:1 row_mask:0xf bank_mask:0xf
	v_mov_b32_dpp v172, v62 row_shr:2 row_mask:0xf bank_mask:0xf
	v_mov_b32_dpp v171, v63 row_shr:1 row_mask:0xf bank_mask:0xf
	v_mov_b32_dpp v173, v63 row_shr:2 row_mask:0xf bank_mask:0xf
	v_mov_b32_dpp v174, v64 row_shr:1 row_mask:0xf bank_mask:0xf
	v_mov_b32_dpp v176, v64 row_shr:2 row_mask:0xf bank_mask:0xf
	v_mov_b32_dpp v175, v65 row_shr:1 row_mask:0xf bank_mask:0xf
	v_mov_b32_dpp v177, v65 row_shr:2 row_mask:0xf bank_mask:0xf
	v_mov_b32_dpp v198, v58 row_shr:1 row_mask:0xf bank_mask:0xf
	v_mov_b32_dpp v200, v58 row_shr:2 row_mask:0xf bank_mask:0xf
	v_mov_b32_dpp v199, v59 row_shr:1 row_mask:0xf bank_mask:0xf
	v_mov_b32_dpp v201, v59 row_shr:2 row_mask:0xf bank_mask:0xf
	v_mov_b32_dpp v202, v60 row_shr:1 row_mask:0xf bank_mask:0xf
	v_mov_b32_dpp v204, v60 row_shr:2 row_mask:0xf bank_mask:0xf
	v_mov_b32_dpp v203, v61 row_shr:1 row_mask:0xf bank_mask:0xf
	v_mov_b32_dpp v205, v61 row_shr:2 row_mask:0xf bank_mask:0xf
	s_and_saveexec_b64 s[56:57], s[42:43]
	s_xor_b64 s[56:57], exec, s[56:57]
	s_cbranch_execz .LBB0_363
	v_pk_fma_f32 v[204:205], v[132:133], v[204:205], v[144:145]
	v_pk_fma_f32 v[200:201], v[130:131], v[200:201], v[142:143]
	v_pk_fma_f32 v[202:203], v[136:137], v[202:203], v[204:205]
	v_pk_fma_f32 v[198:199], v[134:135], v[198:199], v[200:201]
	v_pk_fma_f32 v[202:203], v[60:61], v[140:141], v[202:203]
	v_pk_fma_f32 v[198:199], v[58:59], v[138:139], v[198:199]
	v_mul_f32_e32 v197, 0xbfb8aa3b, v202
	v_mul_f32_e32 v204, 0xbfb8aa3b, v203
	v_exp_f32_e32 v197, v197
	v_exp_f32_e32 v204, v204
	v_pk_fma_f32 v[176:177], v[148:149], v[176:177], v[160:161]
	v_pk_fma_f32 v[172:173], v[146:147], v[172:173], v[158:159]
	v_add_f32_e32 v197, 1.0, v197
	v_add_f32_e32 v205, 1.0, v204
	v_rcp_f32_e32 v204, v197
	v_rcp_f32_e32 v205, v205
	v_mul_f32_e32 v197, 0xbfb8aa3b, v198
	v_exp_f32_e32 v197, v197
	v_pk_fma_f32 v[174:175], v[152:153], v[174:175], v[176:177]
	v_pk_mul_f32 v[200:201], v[202:203], v[204:205]
	v_mul_f32_e32 v202, 0xbfb8aa3b, v199
	v_exp_f32_e32 v203, v202
	v_add_f32_e32 v197, 1.0, v197
	v_pk_fma_f32 v[174:175], v[64:65], v[156:157], v[174:175]
	v_pk_fma_f32 v[170:171], v[150:151], v[170:171], v[172:173]
	v_rcp_f32_e32 v202, v197
	v_add_f32_e32 v197, 1.0, v203
	v_mul_f32_e32 v176, 0xbfb8aa3b, v174
	v_pk_fma_f32 v[170:171], v[62:63], v[154:155], v[170:171]
	v_rcp_f32_e32 v203, v197
	v_exp_f32_e32 v197, v176
	v_mul_f32_e32 v176, 0xbfb8aa3b, v175
	v_mul_f32_e32 v172, 0xbfb8aa3b, v170
	v_mul_f32_e32 v173, 0xbfb8aa3b, v171
	v_exp_f32_e32 v204, v176
	v_exp_f32_e32 v172, v172
	v_exp_f32_e32 v173, v173
	v_add_f32_e32 v197, 1.0, v197
	v_pk_mul_f32 v[176:177], v[198:199], v[202:203]
	v_rcp_f32_e32 v198, v197
	v_add_f32_e32 v197, 1.0, v204
	v_add_f32_e32 v172, 1.0, v172
	v_add_f32_e32 v173, 1.0, v173
	v_rcp_f32_e32 v199, v197
	v_rcp_f32_e32 v172, v172
	v_rcp_f32_e32 v173, v173
	v_pk_mul_f32 v[200:201], v[44:45], v[200:201]
	v_pk_mul_f32 v[174:175], v[174:175], v[198:199]
	v_pk_mul_f32 v[176:177], v[42:43], v[176:177]
	v_pk_mul_f32 v[170:171], v[170:171], v[172:173]
	v_pk_mul_f32 v[174:175], v[48:49], v[174:175]
	v_pk_mul_f32 v[170:171], v[46:47], v[170:171]
	v_cvt_pk_bf16_f32 v172, v176, v177
	v_cvt_pk_bf16_f32 v170, v170, v171
	v_cvt_pk_bf16_f32 v171, v174, v175
	v_mov_b64_e32 v[174:175], s[24:25]
	v_mad_i64_i32 v[174:175], s[68:69], v0, s15, v[174:175]
	v_cvt_pk_bf16_f32 v173, v200, v201
	v_lshl_add_u64 v[174:175], v[162:163], 1, v[174:175]
	global_store_dwordx4 v[174:175], v[170:173], off

.LBB0_373:
	s_or_b64 exec, exec, s[48:49]
.Lhu_skip_ai1:
	s_mov_b64 s[48:49], 0
